# mixer staging loops unrolled (GLU, ssm_gemm_rows both paths, ssm_sgemm): global loads in flight before LDS writes; gate poll overlaps its L1 invalidate
# speedup vs baseline: 1.0044x; 1.0044x over previous
;     __device__ __forceinline__ void a_ready(const Unit& u) const {
;     ...
;             const unsigned long long t0 = __builtin_amdgcn_s_memrealtime(); unsigned polls = 0;
;             while ((unsigned)__builtin_amdgcn_readfirstlane(__hip_atomic_load(ready, __ATOMIC_RELAXED, __HIP_MEMORY_SCOPE_AGENT)) < need) {
;                 if ((++polls & 255u) == 0u && __builtin_amdgcn_readfirstlane(__hip_atomic_load(tmo, __ATOMIC_RELAXED, __HIP_MEMORY_SCOPE_AGENT)) != 0u) break;
;                 if (__builtin_amdgcn_s_memrealtime() - t0 > 2000000ull) {
;                     if (threadIdx.x == 0) { unsigned expect = 0u; __hip_atomic_compare_exchange_strong(tmo + 1, &expect, 0x600u | (unsigned)(u.pm & 0xff), __ATOMIC_RELAXED, __ATOMIC_RELAXED, __HIP_MEMORY_SCOPE_AGENT); __hip_atomic_store(tmo, 1u, __ATOMIC_RELAXED, __HIP_MEMORY_SCOPE_AGENT); }
;                     break; }
;                 __builtin_amdgcn_s_sleep(2); }
;             __builtin_amdgcn_fence(__ATOMIC_ACQUIRE, "agent");
.LBB0_570:
	buffer_inv sc1
	global_load_dword v138, v195, s[4:5] sc1
	s_mov_b64 s[36:37], -1
	s_waitcnt vmcnt(0)
	v_readfirstlane_b32 s38, v138
	s_cmp_ge_u32 s38, s33
	s_mov_b64 s[38:39], -1
	s_cbranch_scc1 .LBB0_569
	s_and_b32 s36, s57, 0xff
	s_cmp_lg_u32 s36, 0
	s_cselect_b64 s[38:39], -1, 0
	s_cmp_eq_u32 s36, 0
	s_cbranch_scc1 .LBB0_573
	s_mov_b64 s[36:37], -1
	s_andn2_b64 vcc, exec, s[38:39]
	s_mov_b64 s[38:39], -1
	s_cbranch_vccnz .LBB0_569
	s_branch .LBB0_574

;     __device__ __forceinline__ void a_ready(const Unit& u) const {
;     ...
;             __builtin_amdgcn_fence(__ATOMIC_ACQUIRE, "agent");
;             asm volatile("s_waitcnt vmcnt(0)" ::: "memory");
.LBB0_580:
	s_waitcnt vmcnt(0) lgkmcnt(0)
	s_waitcnt vmcnt(0)

;     __device__ __forceinline__ void a_ready(const Unit& u) const {
;     ...
;             const unsigned long long t0 = __builtin_amdgcn_s_memrealtime(); unsigned polls = 0;
;             while ((unsigned)__builtin_amdgcn_readfirstlane(__hip_atomic_load(ready, __ATOMIC_RELAXED, __HIP_MEMORY_SCOPE_AGENT)) < need) {
;                 if ((++polls & 255u) == 0u && __builtin_amdgcn_readfirstlane(__hip_atomic_load(tmo, __ATOMIC_RELAXED, __HIP_MEMORY_SCOPE_AGENT)) != 0u) break;
;                 if (__builtin_amdgcn_s_memrealtime() - t0 > 2000000ull) {
;                     if (threadIdx.x == 0) { unsigned expect = 0u; __hip_atomic_compare_exchange_strong(tmo + 1, &expect, 0x600u | (unsigned)(u.pm & 0xff), __ATOMIC_RELAXED, __ATOMIC_RELAXED, __HIP_MEMORY_SCOPE_AGENT); __hip_atomic_store(tmo, 1u, __ATOMIC_RELAXED, __HIP_MEMORY_SCOPE_AGENT); }
;                     break; }
;                 __builtin_amdgcn_s_sleep(2); }
;             __builtin_amdgcn_fence(__ATOMIC_ACQUIRE, "agent");
.LBB0_1085:
	buffer_inv sc1
	global_load_dword v138, v195, s[0:1] sc1
	v_readlane_b32 s37, v250, 56
	s_mov_b64 s[34:35], -1
	s_waitcnt vmcnt(0)
	v_readfirstlane_b32 s36, v138
	s_cmp_ge_u32 s36, s37
	s_mov_b64 s[36:37], -1
	s_cbranch_scc1 .LBB0_1084
	s_and_b32 s34, s58, 0xff
	s_cmp_lg_u32 s34, 0
	s_cselect_b64 s[36:37], -1, 0
	s_cmp_eq_u32 s34, 0
	s_cbranch_scc1 .LBB0_1088
	s_mov_b64 s[34:35], -1
	s_andn2_b64 vcc, exec, s[36:37]
	s_mov_b64 s[36:37], -1
	s_cbranch_vccnz .LBB0_1084
	s_branch .LBB0_1089

; #define LAS __attribute__((address_space(3)))
; __device__ __forceinline__ void ssm_sgemm_item(Frame& F, const Args& AR, int l, int item) {
;     ...
;     const bf16* Bt = (const bf16*)(F.ws + WS_SSMWS) + (size_t)(l * 32 + g) * 256 * 256 + (size_t)(F.wave * 32) * K;
;     bf16x8v b0[8][2];
;     wave_bfrags<K>(Bt, 0, b0, F.lane);
;     __syncthreads();
;     for (int idx = F.tid; idx < NROW * 32; idx += NTHR) { const int piece = idx & 1, tok = (idx >> 1) & 15, row = idx >> 5, cr = row0 + row;
;         v4u v = {0u, 0u, 0u, 0u}; if (cr < NCR) v = *(const v4u*)(P + (size_t)(cr * 16 + tok) * DIN + SSM_OFF + g * 16 + piece * 8);
;         *(LAS v4u*)(at + row * LDA + (tok * 16 + piece * 8) * 2) = v; }
; __global__ void __launch_bounds__(NTHR, 2) fwd_kernel(Args args) {
;     ...
;             while (it < W_END) {
;                 { int t_ = threadIdx.x; asm volatile("" : "+v"(t_)); F.tid = t_; F.lane = t_ & 63; F.wave = __builtin_amdgcn_readfirstlane(t_ >> 6); }
;                 if (it < W_ATT) { _Pragma("unroll 1") for (int rr = 0; rr < (PROBE_DUP == 61 ? 2 : 1); ++rr) attn_item_mfma(F, args, l, it); }
;                 else if (it < W_CFFT) fft_item<8>(F, args, it - W_ATT);
;                 else if (it < W_FFT) { _Pragma("unroll 1") for (int rr = 0; rr < (PROBE_DUP == 62 ? 2 : 1); ++rr) fft_item<12>(F, args, it - W_CFFT); }
;                 else if (it < W_CONV) { _Pragma("unroll 1") for (int rr = 0; rr < (PROBE_DUP == 63 ? 2 : 1); ++rr) conv_tile_v1(F, args, l, it - W_FFT); }
;                 else { ssm_sgemm_item(F, args, l, it - W_CONV); if (PROBE_DUP == 64) ssm_sgemm_item(F, args, l, it - W_CONV); }
.LBB0_1270:
	v_mov_b32_e32 v70, v0
	s_mov_b64 s[0:1], -1
	v_readfirstlane_b32 s11, v70
	s_ashr_i32 s12, s11, 6
	v_and_b32_e32 v149, 63, v70
	s_cmpk_gt_i32 s10, 0x10f
	s_cbranch_scc0 .LBB0_1276
	s_cmpk_gt_u32 s10, 0x117
	s_cbranch_scc0 .LBB0_1445
	s_cmpk_gt_u32 s10, 0x197
	s_cbranch_scc0 .LBB0_1370
	s_cmpk_gt_u32 s10, 0x3b7
	s_cbranch_scc0 .LBB0_1349
	s_add_i32 s8, s10, 0xfffffc48
	s_and_b32 s14, s8, 31
	s_lshr_b32 s13, s8, 5
	s_lshl_b32 s0, s14, 17
	v_readlane_b32 s1, v254, 49
	s_lshl_b32 s15, s13, 6
	s_or_b32 s0, s0, s1
	v_readlane_b32 s1, v253, 1
	s_add_u32 s4, s1, s0
	v_readlane_b32 s0, v253, 2
	s_addc_u32 s5, s0, 0
	s_lshl_b32 s0, s12, 5
	s_ashr_i32 s1, s0, 31
	s_lshl_b64 s[0:1], s[0:1], 9
	s_add_u32 s0, s4, s0
	s_addc_u32 s1, s5, s1
	v_and_b32_e32 v72, 48, v70
	v_mov_b32_e32 v73, v195
	v_lshlrev_b32_e32 v4, 9, v149
	v_lshl_add_u64 v[2:3], s[0:1], 0, v[72:73]
	v_and_b32_e32 v194, 0x1e00, v4
	v_lshl_add_u64 v[4:5], v[2:3], 0, v[194:195]
	v_or_b32_e32 v194, 0x2000, v194
	v_lshl_add_u64 v[6:7], v[2:3], 0, v[194:195]
	global_load_dwordx4 v[58:61], v[4:5], off
	global_load_dwordx4 v[50:53], v[4:5], off offset:64
	global_load_dwordx4 v[62:65], v[6:7], off
	global_load_dwordx4 v[54:57], v[6:7], off offset:64
	global_load_dwordx4 v[42:45], v[4:5], off offset:128
	global_load_dwordx4 v[34:37], v[4:5], off offset:192
	global_load_dwordx4 v[46:49], v[6:7], off offset:128
	global_load_dwordx4 v[38:41], v[6:7], off offset:192
	global_load_dwordx4 v[26:29], v[4:5], off offset:256
	global_load_dwordx4 v[18:21], v[4:5], off offset:320
	global_load_dwordx4 v[30:33], v[6:7], off offset:256
	global_load_dwordx4 v[22:25], v[6:7], off offset:320
	global_load_dwordx4 v[10:13], v[4:5], off offset:384
	s_nop 0
	global_load_dwordx4 v[2:5], v[4:5], off offset:448
	s_nop 0
	global_load_dwordx4 v[14:17], v[6:7], off offset:384
	s_nop 0
	global_load_dwordx4 v[6:9], v[6:7], off offset:448
	s_movk_i32 s0, 0x800
	v_cmp_gt_i32_e32 vcc, s0, v70
	s_waitcnt vmcnt(0)
	s_barrier
	s_and_saveexec_b64 s[0:1], vcc
	s_cbranch_execz .LBB0_1306
	s_lshl_b32 s6, s14, 4
	v_readlane_b32 s16, v250, 58
	v_and_b32_e32 v67, 1, v70
	v_readlane_b32 s17, v250, 59
	s_lshl_b32 s16, s6, 1
	v_lshlrev_b32_e32 v66, 3, v67
	v_writelane_b32 v250, s16, 58
	v_lshlrev_b32_e32 v71, 4, v67
	v_writelane_b32 v250, s17, 59
	v_lshlrev_b32_e32 v194, 1, v66
	v_ashrrev_i32_e32 v75, 5, v70
	v_bfe_u32 v74, v70, 1, 4
	v_add_u32_e32 v76, s15, v75
	v_lshl_or_b32 v68, v76, 4, v74
	v_mov_b64_e32 v[66:67], s[90:91]
	v_mad_i64_i32 v[66:67], s[6:7], v68, s25, v[66:67]
	v_lshl_add_u64 v[66:67], v[66:67], 0, s[16:17]
	v_lshl_add_u64 v[66:67], v[66:67], 0, v[194:195]
	v_add_co_u32_e32 v66, vcc, 0x39600000, v66
	s_nop 1
	v_addc_co_u32_e32 v67, vcc, 0, v67, vcc
	s_mov_b64 s[6:7], 0x160000
	global_load_dwordx4 v[78:81], v[66:67], off offset:512
	v_lshl_add_u64 v[66:67], v[66:67], 0, s[6:7]
	global_load_dwordx4 v[82:85], v[66:67], off offset:512
	v_lshl_add_u64 v[66:67], v[66:67], 0, s[6:7]
	global_load_dwordx4 v[86:89], v[66:67], off offset:512
	v_lshl_add_u64 v[66:67], v[66:67], 0, s[6:7]
	global_load_dwordx4 v[90:93], v[66:67], off offset:512
	s_movk_i32 s6, 0x210
	v_mul_lo_u32 v75, v75, s6
	v_lshlrev_b32_e32 v74, 5, v74
	v_add3_u32 v74, v75, v74, v71
	s_waitcnt vmcnt(3)
	v_cmp_gt_i32_e32 vcc, 0x220, v76
	s_nop 1
	v_cndmask_b32_e32 v78, 0, v78, vcc
	v_cndmask_b32_e32 v79, 0, v79, vcc
	v_cndmask_b32_e32 v80, 0, v80, vcc
	v_cndmask_b32_e32 v81, 0, v81, vcc
	ds_write_b128 v74, v[78:81]
	s_waitcnt vmcnt(2)
	v_cmp_gt_i32_e32 vcc, 0x210, v76
	s_nop 1
	v_cndmask_b32_e32 v82, 0, v82, vcc
	v_cndmask_b32_e32 v83, 0, v83, vcc
	v_cndmask_b32_e32 v84, 0, v84, vcc
	v_cndmask_b32_e32 v85, 0, v85, vcc
	ds_write_b128 v74, v[82:85] offset:8448
	s_waitcnt vmcnt(1)
	v_cmp_gt_i32_e32 vcc, 0x200, v76
	s_nop 1
	v_cndmask_b32_e32 v86, 0, v86, vcc
	v_cndmask_b32_e32 v87, 0, v87, vcc
	v_cndmask_b32_e32 v88, 0, v88, vcc
	v_cndmask_b32_e32 v89, 0, v89, vcc
	ds_write_b128 v74, v[86:89] offset:16896
	s_waitcnt vmcnt(0)
	v_cmp_gt_i32_e32 vcc, 0x1f0, v76
	s_nop 1
	v_cndmask_b32_e32 v90, 0, v90, vcc
	v_cndmask_b32_e32 v91, 0, v91, vcc
	v_cndmask_b32_e32 v92, 0, v92, vcc
	v_cndmask_b32_e32 v93, 0, v93, vcc
	ds_write_b128 v74, v[90:93] offset:25344
	s_branch .LBB0_1306

; #define LAS __attribute__((address_space(3)))
; __device__ __forceinline__ unsigned pk2(float lo, float hi) { const f32x2cv v = {lo, hi}; return __builtin_bit_cast(unsigned, __builtin_convertvector(v, bf16x2cv)); }
; __device__ __forceinline__ void attn_item_mfma(Frame& F, const Args& AR, int l, int item) {
;     ...
;         float ps = 0.f;
; #pragma unroll
;         for (int kb = 0; kb < 2; ++kb)
; #pragma unroll
;             for (int r = 0; r < 16; ++r) { st[kb][r] = __builtin_amdgcn_exp2f(st[kb][r] - mnew); ps += st[kb][r]; }
;         lsum = lsum * corr + ps;
;         if (__builtin_amdgcn_ballot_w64(corr != 1.0f) != 0ull) {
; #pragma unroll
;             for (int db = 0; db < 2; ++db)
; #pragma unroll
;                 for (int r = 0; r < 16; ++r) o[db][r] *= corr; }
; #pragma unroll
;         for (int m = 0; m < 4; ++m) { const int kb = m >> 1, r0 = 8 * (m & 1); v4u pw;
;             pw.x = pk2(st[kb][r0 + 0], st[kb][r0 + 1]); pw.y = pk2(st[kb][r0 + 2], st[kb][r0 + 3]); pw.z = pk2(st[kb][r0 + 4], st[kb][r0 + 5]); pw.w = pk2(st[kb][r0 + 6], st[kb][r0 + 7]);
;             const bf16x8v pf = __builtin_bit_cast(bf16x8v, pw);
; #pragma unroll
;             for (int db = 0; db < 2; ++db) { const LAS unsigned char* vp = vb_ + (32 * db + r32) * AT_ROW + (16 * m + 4 * hi) * 2;
;                 const v2u lo = *(const LAS v2u*)vp, hh = *(const LAS v2u*)(vp + 16); const v4u w = {lo.x, lo.y, hh.x, hh.y};
;                 o[db] = __builtin_amdgcn_mfma_f32_32x32x16_bf16(__builtin_bit_cast(bf16x8v, w), pf, o[db], 0, 0, 0); } }
;     }
.LBB0_1300:
	v_sub_f32_e32 v50, v50, v101
	v_exp_f32_e32 v50, v50
	v_sub_f32_e32 v51, v51, v101
	v_exp_f32_e32 v51, v51
	v_sub_f32_e32 v52, v52, v101
	v_exp_f32_e32 v52, v52
	v_sub_f32_e32 v53, v53, v101
	v_exp_f32_e32 v53, v53
	v_sub_f32_e32 v54, v54, v101
	v_add_f32_e32 v99, 0, v50
	v_exp_f32_e32 v54, v54
	v_sub_f32_e32 v55, v55, v101
	v_add_f32_e32 v99, v51, v99
	v_exp_f32_e32 v55, v55
	v_sub_f32_e32 v56, v56, v101
	v_add_f32_e32 v99, v52, v99
	v_exp_f32_e32 v56, v56
	v_sub_f32_e32 v57, v57, v101
	v_add_f32_e32 v99, v53, v99
	v_exp_f32_e32 v57, v57
	v_sub_f32_e32 v58, v58, v101
	v_add_f32_e32 v99, v54, v99
	v_exp_f32_e32 v58, v58
	v_sub_f32_e32 v59, v59, v101
	v_add_f32_e32 v99, v55, v99
	v_exp_f32_e32 v59, v59
	v_sub_f32_e32 v60, v60, v101
	v_add_f32_e32 v99, v56, v99
	v_exp_f32_e32 v60, v60
	v_sub_f32_e32 v61, v61, v101
	v_add_f32_e32 v99, v57, v99
	v_exp_f32_e32 v61, v61
	v_sub_f32_e32 v62, v62, v101
	v_add_f32_e32 v99, v58, v99
	v_exp_f32_e32 v62, v62
	v_sub_f32_e32 v63, v63, v101
	v_add_f32_e32 v99, v59, v99
	v_exp_f32_e32 v63, v63
	v_sub_f32_e32 v64, v64, v101
	v_add_f32_e32 v99, v60, v99
	v_exp_f32_e32 v64, v64
	v_sub_f32_e32 v65, v65, v101
	v_add_f32_e32 v99, v61, v99
	v_exp_f32_e32 v65, v65
	v_sub_f32_e32 v34, v34, v101
	v_add_f32_e32 v99, v62, v99
	v_exp_f32_e32 v112, v34
	v_add_f32_e32 v99, v63, v99
	v_add_f32_e32 v99, v64, v99
	v_add_f32_e32 v99, v65, v99
	v_sub_f32_e32 v36, v36, v101
	v_add_f32_e32 v34, v112, v99
	v_exp_f32_e32 v99, v36
	v_sub_f32_e32 v36, v37, v101
	v_exp_f32_e32 v113, v36
	v_sub_f32_e32 v36, v38, v101
	v_exp_f32_e32 v114, v36
	v_sub_f32_e32 v36, v39, v101
	v_exp_f32_e32 v115, v36
	v_sub_f32_e32 v36, v40, v101
	v_exp_f32_e32 v116, v36
	v_sub_f32_e32 v36, v41, v101
	v_exp_f32_e32 v117, v36
	v_sub_f32_e32 v36, v42, v101
	v_exp_f32_e32 v118, v36
	v_sub_f32_e32 v36, v43, v101
	v_exp_f32_e32 v119, v36
	v_sub_f32_e32 v36, v44, v101
	v_exp_f32_e32 v120, v36
	v_sub_f32_e32 v36, v45, v101
	v_exp_f32_e32 v121, v36
	v_sub_f32_e32 v36, v46, v101
	v_exp_f32_e32 v122, v36
	v_sub_f32_e32 v36, v47, v101
	v_exp_f32_e32 v123, v36
	v_sub_f32_e32 v36, v48, v101
	v_exp_f32_e32 v48, v36
	v_sub_f32_e32 v36, v49, v101
	v_exp_f32_e32 v49, v36
	v_cvt_pk_bf16_f32 v36, v50, v51
	v_add3_u32 v50, s93, v97, v109
	v_add_u32_e32 v51, 0x2000, v50
	ds_read2_b64 v[40:43], v51 offset0:128 offset1:130
	ds_read2_b64 v[44:47], v51 offset0:132 offset1:134
	v_cvt_pk_bf16_f32 v37, v52, v53
	v_cvt_pk_bf16_f32 v38, v54, v55
	v_cvt_pk_bf16_f32 v39, v56, v57
	v_add_u32_e32 v50, 0x3000, v50
	v_sub_f32_e32 v35, v35, v101
	s_waitcnt lgkmcnt(1)
	v_mfma_f32_32x32x16_bf16 v[18:33], v[40:43], v[36:39], v[18:33]
	ds_read2_b64 v[40:43], v50 offset0:192 offset1:194
	v_exp_f32_e32 v35, v35
	s_add_i32 s84, s84, 1
	s_add_i32 s90, s90, 64
	s_add_i32 s88, s88, 64
	v_add_f32_e32 v34, v35, v34
	v_add_f32_e32 v34, v99, v34
	s_waitcnt lgkmcnt(0)
	v_mfma_f32_32x32x16_bf16 v[2:17], v[40:43], v[36:39], v[2:17]
	ds_read2_b64 v[40:43], v50 offset0:196 offset1:198
	v_cvt_pk_bf16_f32 v36, v58, v59
	v_cvt_pk_bf16_f32 v37, v60, v61
	v_cvt_pk_bf16_f32 v38, v62, v63
	v_cvt_pk_bf16_f32 v39, v64, v65
	v_add_f32_e32 v34, v113, v34
	v_add_f32_e32 v34, v114, v34
	s_waitcnt lgkmcnt(0)
	v_mfma_f32_32x32x16_bf16 v[2:17], v[40:43], v[36:39], v[2:17]
	ds_read2_b64 v[40:43], v51 offset0:136 offset1:138
	v_add_f32_e32 v34, v115, v34
	v_add_f32_e32 v34, v116, v34
	v_add_f32_e32 v34, v117, v34
	v_add_f32_e32 v34, v118, v34
	v_add_f32_e32 v34, v119, v34
	v_add_f32_e32 v34, v120, v34
	v_mfma_f32_32x32x16_bf16 v[18:33], v[44:47], v[36:39], v[18:33]
	v_cvt_pk_bf16_f32 v36, v112, v35
	v_cvt_pk_bf16_f32 v37, v99, v113
	v_cvt_pk_bf16_f32 v38, v114, v115
	v_cvt_pk_bf16_f32 v39, v116, v117
	v_add_f32_e32 v34, v121, v34
	v_add_f32_e32 v34, v122, v34
	v_add_f32_e32 v34, v123, v34
	s_waitcnt lgkmcnt(0)
	v_mfma_f32_32x32x16_bf16 v[18:33], v[40:43], v[36:39], v[18:33]
	ds_read2_b64 v[40:43], v50 offset0:200 offset1:202
	v_add_f32_e32 v34, v48, v34
	v_add_f32_e32 v34, v49, v34
	v_fmac_f32_e32 v34, v111, v102
	s_cmp_lg_u32 s91, s84
	s_waitcnt lgkmcnt(0)
	v_mfma_f32_32x32x16_bf16 v[2:17], v[40:43], v[36:39], v[2:17]
	ds_read2_b64 v[40:43], v51 offset0:140 offset1:142
	v_cvt_pk_bf16_f32 v36, v118, v119
	v_cvt_pk_bf16_f32 v37, v120, v121
	v_cvt_pk_bf16_f32 v38, v122, v123
	v_cvt_pk_bf16_f32 v39, v48, v49
	s_waitcnt lgkmcnt(0)
	s_nop 0
	v_mfma_f32_32x32x16_bf16 v[18:33], v[40:43], v[36:39], v[18:33]
	ds_read2_b64 v[40:43], v50 offset0:204 offset1:206
	s_waitcnt lgkmcnt(0)
	v_mfma_f32_32x32x16_bf16 v[2:17], v[40:43], v[36:39], v[2:17]
	s_cbranch_scc0 .LBB0_1305
	v_mov_b32_e32 v111, v34
	v_mov_b32_e32 v99, v101
	s_branch .LBB0_1284
; __device__ __forceinline__ unsigned pk2(float lo, float hi) { const f32x2cv v = {lo, hi}; return __builtin_bit_cast(unsigned, __builtin_convertvector(v, bf16x2cv)); }
; __device__ __forceinline__ void attn_item_mfma(Frame& F, const Args& AR, int l, int item) {
;     ...
;     {
;         const float lt = lsum + __shfl_xor(lsum, 32), inv = 1.0f / lt;
;         bf16* op = CAT + (size_t)qrow * DM + h * 64;
; #pragma unroll
;         for (int db = 0; db < 2; ++db)
; #pragma unroll
;             for (int rq = 0; rq < 4; ++rq) { v2u w; w.x = pk2(o[db][4 * rq] * inv, o[db][4 * rq + 1] * inv); w.y = pk2(o[db][4 * rq + 2] * inv, o[db][4 * rq + 3] * inv);
;                 *(v2u*)(op + 32 * db + 8 * rq + 4 * hi) = w; }
;     }
.LBB0_1305:
	ds_bpermute_b32 v35, v107, v34
	v_readlane_b32 s0, v250, 52
	v_lshlrev_b64 v[36:37], 12, v[94:95]
	v_readlane_b32 s1, v250, 53
	v_lshlrev_b32_e32 v194, 1, v103
	s_waitcnt lgkmcnt(0)
	v_add_f32_e32 v38, v34, v35
	v_lshl_add_u64 v[36:37], s[0:1], 0, v[36:37]
	v_div_scale_f32 v39, s[0:1], v38, v38, 1.0
	v_rcp_f32_e32 v40, v39
	v_readlane_b32 s0, v254, 55
	v_readlane_b32 s1, v254, 56
	v_readlane_b32 s64, v250, 18
	v_readlane_b32 s72, v250, 26
	v_lshl_add_u64 v[34:35], s[0:1], 1, v[36:37]
	v_fma_f32 v37, -v39, v40, 1.0
	v_div_scale_f32 v36, vcc, 1.0, v38, 1.0
	v_fmac_f32_e32 v40, v37, v40
	v_mul_f32_e32 v37, v36, v40
	v_fma_f32 v41, -v39, v37, v36
	v_fmac_f32_e32 v37, v41, v40
	v_fma_f32 v36, -v39, v37, v36
	v_div_fmas_f32 v36, v36, v40, v37
	v_div_fixup_f32 v36, v36, v38, 1.0
	v_pk_mul_f32 v[18:19], v[18:19], v[36:37] op_sel_hi:[1,0]
	v_pk_mul_f32 v[20:21], v[20:21], v[36:37] op_sel_hi:[1,0]
	v_pk_mul_f32 v[2:3], v[2:3], v[36:37] op_sel_hi:[1,0]
	v_pk_mul_f32 v[4:5], v[4:5], v[36:37] op_sel_hi:[1,0]
	v_lshl_add_u64 v[34:35], v[34:35], 0, v[194:195]
	v_cvt_pk_bf16_f32 v18, v18, v19
	v_cvt_pk_bf16_f32 v19, v20, v21
	v_cvt_pk_bf16_f32 v2, v2, v3
	v_cvt_pk_bf16_f32 v3, v4, v5
	global_store_dwordx2 v[34:35], v[18:19], off
	v_pk_mul_f32 v[18:19], v[22:23], v[36:37] op_sel_hi:[1,0]
	v_pk_mul_f32 v[20:21], v[24:25], v[36:37] op_sel_hi:[1,0]
	global_store_dwordx2 v[34:35], v[2:3], off offset:64
	v_pk_mul_f32 v[2:3], v[6:7], v[36:37] op_sel_hi:[1,0]
	v_pk_mul_f32 v[4:5], v[8:9], v[36:37] op_sel_hi:[1,0]
	v_cvt_pk_bf16_f32 v18, v18, v19
	v_cvt_pk_bf16_f32 v19, v20, v21
	v_cvt_pk_bf16_f32 v2, v2, v3
	v_cvt_pk_bf16_f32 v3, v4, v5
	global_store_dwordx2 v[34:35], v[18:19], off offset:16
	v_pk_mul_f32 v[18:19], v[26:27], v[36:37] op_sel_hi:[1,0]
	v_pk_mul_f32 v[20:21], v[28:29], v[36:37] op_sel_hi:[1,0]
	global_store_dwordx2 v[34:35], v[2:3], off offset:80
	v_pk_mul_f32 v[2:3], v[10:11], v[36:37] op_sel_hi:[1,0]
	v_pk_mul_f32 v[4:5], v[12:13], v[36:37] op_sel_hi:[1,0]
	v_cvt_pk_bf16_f32 v18, v18, v19
	v_cvt_pk_bf16_f32 v19, v20, v21
	v_cvt_pk_bf16_f32 v2, v2, v3
	v_cvt_pk_bf16_f32 v3, v4, v5
	v_readlane_b32 s73, v250, 27
	v_readlane_b32 s74, v250, 28
	v_readlane_b32 s75, v250, 29
	v_readlane_b32 s78, v250, 32
	v_readlane_b32 s79, v250, 33
	global_store_dwordx2 v[34:35], v[18:19], off offset:32
	v_pk_mul_f32 v[18:19], v[30:31], v[36:37] op_sel_hi:[1,0]
	v_pk_mul_f32 v[20:21], v[32:33], v[36:37] op_sel_hi:[1,0]
	global_store_dwordx2 v[34:35], v[2:3], off offset:96
	v_pk_mul_f32 v[2:3], v[14:15], v[36:37] op_sel_hi:[1,0]
	v_pk_mul_f32 v[4:5], v[16:17], v[36:37] op_sel_hi:[1,0]
	v_readlane_b32 s84, v254, 19
	v_readlane_b32 s82, v254, 27
	v_readlane_b32 s76, v250, 30
	v_readlane_b32 s77, v250, 31
	v_readlane_b32 s92, v250, 50
	v_readlane_b32 s94, v254, 29
	v_readlane_b32 s96, v254, 31
	v_readlane_b32 s72, v254, 33
	v_readlane_b32 s74, v254, 35
	v_readlane_b32 s78, v254, 37
	v_readlane_b32 s34, v254, 40
	v_cvt_pk_bf16_f32 v18, v18, v19
	v_cvt_pk_bf16_f32 v19, v20, v21
	v_cvt_pk_bf16_f32 v2, v2, v3
	v_cvt_pk_bf16_f32 v3, v4, v5
	v_readlane_b32 s80, v254, 18
	v_readlane_b32 s85, v254, 20
	v_readlane_b32 s86, v254, 21
	v_readlane_b32 s87, v254, 22
	v_readlane_b32 s88, v254, 23
	v_readlane_b32 s89, v254, 24
	v_readlane_b32 s90, v254, 25
	v_readlane_b32 s91, v254, 26
	v_readlane_b32 s83, v254, 28
	v_readlane_b32 s65, v250, 19
	v_readlane_b32 s66, v250, 20
	v_readlane_b32 s67, v250, 21
	v_readlane_b32 s68, v250, 22
	v_readlane_b32 s69, v250, 23
	v_readlane_b32 s70, v250, 24
	v_readlane_b32 s71, v250, 25
	v_readlane_b32 s93, v250, 51
	v_readlane_b32 s81, v254, 54
	v_readlane_b32 s95, v254, 30
	v_readlane_b32 s97, v254, 32
	v_readlane_b32 s73, v254, 34
	v_readlane_b32 s75, v254, 36
	s_movk_i32 s76, 0xbc
	v_readlane_b32 s79, v254, 38
	v_readlane_b32 s77, v254, 39
	v_readlane_b32 s35, v254, 41
	s_movk_i32 s25, 0x1600
	s_movk_i32 s24, 0x410
	v_readlane_b32 s14, v254, 14
	global_store_dwordx2 v[34:35], v[18:19], off offset:48
	global_store_dwordx2 v[34:35], v[2:3], off offset:112
	s_and_saveexec_b64 s[0:1], s[92:93]
	s_cbranch_execnz .LBB0_1517
	s_branch .LBB0_1518

; #define LAS __attribute__((address_space(3)))
; template <int PH, int MT> __device__ __forceinline__ void ssm_gemm_rows(Frame& F, const Args& AR, int l, int g, int row0) {
;     ...
;     for (int idx = F.tid; idx < NROW * 32; idx += NTHR) { const int piece = idx & 1, tok = (idx >> 1) & 15, row = idx >> 5, cr = row0 + row;
;         v4u v = {0u, 0u, 0u, 0u}; if (cr < NCR) v = *(const v4u*)(P + (size_t)(cr * 16 + tok) * DIN + SSM_OFF + g * 16 + piece * 8);
;         *(LAS v4u*)(at + row * LDA + (tok * 16 + piece * 8) * 2) = v; }
.LBB0_1587:
	s_or_b64 exec, exec, s[0:1]
	s_and_saveexec_b64 s[0:1], s[46:47]
	s_cbranch_execz .LBB0_1590
	s_lshl_b32 s6, s16, 4
	s_lshl_b32 s8, s6, 1
	v_bfe_u32 v19, v131, 1, 4
	v_ashrrev_i32_e32 v24, 5, v131
	v_lshl_or_b32 v22, v24, 4, v19
	v_mov_b64_e32 v[20:21], s[90:91]
	v_add_u32_e32 v22, 0x1c00, v22
	v_mad_i64_i32 v[20:21], s[6:7], v22, s25, v[20:21]
	v_lshlrev_b32_e32 v194, 1, v136
	v_lshl_add_u64 v[20:21], v[20:21], 0, s[8:9]
	v_lshl_add_u64 v[20:21], v[20:21], 0, v[194:195]
	v_add_co_u32_e32 v20, vcc, 0x39600000, v20
	s_nop 1
	v_addc_co_u32_e32 v21, vcc, 0, v21, vcc
	s_mov_b64 s[4:5], 0x160000
	global_load_dwordx4 v[96:99], v[20:21], off offset:512
	v_lshl_add_u64 v[20:21], v[20:21], 0, s[4:5]
	global_load_dwordx4 v[100:103], v[20:21], off offset:512
	v_lshl_add_u64 v[20:21], v[20:21], 0, s[4:5]
	global_load_dwordx4 v[114:117], v[20:21], off offset:512
	v_lshl_add_u64 v[20:21], v[20:21], 0, s[4:5]
	global_load_dwordx4 v[118:121], v[20:21], off offset:512
	v_lshl_add_u64 v[20:21], v[20:21], 0, s[4:5]
	global_load_dwordx4 v[122:125], v[20:21], off offset:512
	v_lshl_add_u64 v[20:21], v[20:21], 0, s[4:5]
	global_load_dwordx4 v[126:129], v[20:21], off offset:512
	v_mul_lo_u32 v24, v24, s24
	v_lshlrev_b32_e32 v19, 5, v19
	v_add3_u32 v19, v24, v19, v182
	v_add_u32_e32 v18, 0x10400, v19
	s_waitcnt vmcnt(5)
	ds_write_b128 v19, v[96:99]
	s_waitcnt vmcnt(4)
	ds_write_b128 v19, v[100:103] offset:16640
	s_waitcnt vmcnt(3)
	ds_write_b128 v19, v[114:117] offset:33280
	s_waitcnt vmcnt(2)
	ds_write_b128 v19, v[118:121] offset:49920
	s_waitcnt vmcnt(1)
	ds_write_b128 v18, v[122:125]
	s_waitcnt vmcnt(0)
	ds_write_b128 v18, v[126:129] offset:16640

; #define LAS __attribute__((address_space(3)))
; template <int PH, int MT> __device__ __forceinline__ void ssm_gemm_rows(Frame& F, const Args& AR, int l, int g, int row0) {
;     ...
;     for (int idx = F.tid; idx < NROW * 32; idx += NTHR) { const int piece = idx & 1, tok = (idx >> 1) & 15, row = idx >> 5, cr = row0 + row;
;         v4u v = {0u, 0u, 0u, 0u}; if (cr < NCR) v = *(const v4u*)(P + (size_t)(cr * 16 + tok) * DIN + SSM_OFF + g * 16 + piece * 8);
;         *(LAS v4u*)(at + row * LDA + (tok * 16 + piece * 8) * 2) = v; }
.LBB0_1608:
	s_or_b64 exec, exec, s[0:1]
	s_lshl_b32 s8, s17, 6
	s_and_saveexec_b64 s[0:1], s[50:51]
	s_movk_i32 s9, 0x5ff
	s_cbranch_execz .LBB0_1611
	s_lshl_b32 s6, s16, 4
	s_lshl_b32 s20, s6, 1
	v_ashrrev_i32_e32 v76, 5, v131
	v_bfe_u32 v71, v131, 1, 4
	v_add_u32_e32 v74, s8, v76
	v_mov_b64_e32 v[72:73], s[90:91]
	v_lshl_or_b32 v74, v74, 4, v71
	v_mad_i64_i32 v[72:73], s[6:7], v74, s25, v[72:73]
	v_lshlrev_b32_e32 v194, 1, v136
	v_lshl_add_u64 v[72:73], v[72:73], 0, s[20:21]
	v_lshl_add_u64 v[72:73], v[72:73], 0, v[194:195]
	v_add_co_u32_e32 v72, vcc, 0x39600000, v72
	s_nop 1
	v_addc_co_u32_e32 v73, vcc, 0, v73, vcc
	s_mov_b64 s[4:5], 0x160000
	global_load_dwordx4 v[78:81], v[72:73], off offset:512
	v_lshl_add_u64 v[72:73], v[72:73], 0, s[4:5]
	global_load_dwordx4 v[82:85], v[72:73], off offset:512
	v_lshl_add_u64 v[72:73], v[72:73], 0, s[4:5]
	global_load_dwordx4 v[86:89], v[72:73], off offset:512
	v_lshl_add_u64 v[72:73], v[72:73], 0, s[4:5]
	global_load_dwordx4 v[90:93], v[72:73], off offset:512
	v_mul_lo_u32 v76, v76, s24
	v_lshlrev_b32_e32 v71, 5, v71
	v_add3_u32 v71, v76, v71, v182
	s_waitcnt vmcnt(3)
	ds_write_b128 v71, v[78:81]
	s_waitcnt vmcnt(2)
	ds_write_b128 v71, v[82:85] offset:16640
	s_waitcnt vmcnt(1)
	ds_write_b128 v71, v[86:89] offset:33280
	s_waitcnt vmcnt(0)
	ds_write_b128 v71, v[90:93] offset:49920
